# v35 + adaLN GEMV item: the nine SiLU(c) input loads issued together instead of one serialized round trip each
# speedup vs baseline: 1.0016x; 1.0016x over previous
; #define ARGP(i) ka_ptr(ka, (i) * 8)
; __global__ void __launch_bounds__(NWAVES * 64, 2) fwd_kernel(Args args_unused) {
;     ...
;                 const int cb = r % 96, kc = r / 96, col = cb * 64 + lane, k0 = kc * 64;
;                 const float* cin = ARGP(I_C); const float* cc = ARGP(I_CCTX);
;                 for (int idx = lane; idx < 9 * 64; idx += 64) { const int bb = idx >> 6, kk = idx & 63; const float v = (bb < 8) ? cin[bb * DM + k0 + kk] : cc[k0 + kk]; scr[idx] = v / (1.0f + __expf(-v)); }
;                 asm volatile("s_waitcnt lgkmcnt(0)" ::: "memory");
.LBB0_100:
	s_mul_hi_i32 s12, s90, 0x2aaaaaab
	s_lshr_b32 s13, s12, 31
	s_ashr_i32 s60, s12, 4
	s_add_i32 s60, s60, s13
	s_load_dwordx2 s[12:13], s[96:97], 8
	s_waitcnt lgkmcnt(0)
	s_load_dwordx2 s[18:19], s[96:97], 24
	s_waitcnt lgkmcnt(0)
	s_lshl_b32 s34, s60, 6
	s_and_saveexec_b64 s[14:15], s[6:7]
	s_cbranch_execz .LBB0_105
	s_waitcnt lgkmcnt(0)
	v_or_b32_e32 v34, s34, v114
	v_ashrrev_i32_e32 v35, 31, v34
	v_lshlrev_b32_e32 v33, 2, v34
	v_lshl_add_u64 v[34:35], v[34:35], 2, s[18:19]
	global_load_dword v246, v33, s[12:13] nt
	v_add_u32_e32 v37, 0x1000, v33
	global_load_dword v247, v37, s[12:13] nt
	v_add_u32_e32 v37, 0x2000, v33
	global_load_dword v248, v37, s[12:13] nt
	v_add_u32_e32 v37, 0x3000, v33
	global_load_dword v249, v37, s[12:13] nt
	v_add_u32_e32 v37, 0x4000, v33
	global_load_dword v250, v37, s[12:13] nt
	v_add_u32_e32 v37, 0x5000, v33
	global_load_dword v251, v37, s[12:13] nt
	v_add_u32_e32 v37, 0x6000, v33
	global_load_dword v252, v37, s[12:13] nt
	v_add_u32_e32 v37, 0x7000, v33
	global_load_dword v253, v37, s[12:13] nt
	global_load_dword v254, v[34:35], off nt
	s_waitcnt vmcnt(8)
	v_mul_f32_e32 v36, 0xbfb8aa3b, v246
	v_exp_f32_e32 v36, v36
	s_nop 0
	v_add_f32_e32 v31, 1.0, v36
	v_div_scale_f32 v36, s[20:21], v31, v31, v246
	v_rcp_f32_e32 v38, v36
	v_div_scale_f32 v39, vcc, v246, v31, v246
	v_fma_f32 v40, -v36, v38, 1.0
	v_fmac_f32_e32 v38, v40, v38
	v_mul_f32_e32 v40, v39, v38
	v_fma_f32 v41, -v36, v40, v39
	v_fmac_f32_e32 v40, v41, v38
	v_fma_f32 v36, -v36, v40, v39
	v_div_fmas_f32 v36, v36, v38, v40
	v_div_fixup_f32 v31, v36, v31, v246
	ds_write_b32 v116, v31
	s_waitcnt vmcnt(7)
	v_mul_f32_e32 v36, 0xbfb8aa3b, v247
	v_exp_f32_e32 v36, v36
	s_nop 0
	v_add_f32_e32 v31, 1.0, v36
	v_div_scale_f32 v36, s[20:21], v31, v31, v247
	v_rcp_f32_e32 v38, v36
	v_div_scale_f32 v39, vcc, v247, v31, v247
	v_fma_f32 v40, -v36, v38, 1.0
	v_fmac_f32_e32 v38, v40, v38
	v_mul_f32_e32 v40, v39, v38
	v_fma_f32 v41, -v36, v40, v39
	v_fmac_f32_e32 v40, v41, v38
	v_fma_f32 v36, -v36, v40, v39
	v_div_fmas_f32 v36, v36, v38, v40
	v_div_fixup_f32 v31, v36, v31, v247
	ds_write_b32 v116, v31 offset:256
	s_waitcnt vmcnt(6)
	v_mul_f32_e32 v36, 0xbfb8aa3b, v248
	v_exp_f32_e32 v36, v36
	s_nop 0
	v_add_f32_e32 v31, 1.0, v36
	v_div_scale_f32 v36, s[20:21], v31, v31, v248
	v_rcp_f32_e32 v38, v36
	v_div_scale_f32 v39, vcc, v248, v31, v248
	v_fma_f32 v40, -v36, v38, 1.0
	v_fmac_f32_e32 v38, v40, v38
	v_mul_f32_e32 v40, v39, v38
	v_fma_f32 v41, -v36, v40, v39
	v_fmac_f32_e32 v40, v41, v38
	v_fma_f32 v36, -v36, v40, v39
	v_div_fmas_f32 v36, v36, v38, v40
	v_div_fixup_f32 v31, v36, v31, v248
	ds_write_b32 v116, v31 offset:512
	s_waitcnt vmcnt(5)
	v_mul_f32_e32 v36, 0xbfb8aa3b, v249
	v_exp_f32_e32 v36, v36
	s_nop 0
	v_add_f32_e32 v31, 1.0, v36
	v_div_scale_f32 v36, s[20:21], v31, v31, v249
	v_rcp_f32_e32 v38, v36
	v_div_scale_f32 v39, vcc, v249, v31, v249
	v_fma_f32 v40, -v36, v38, 1.0
	v_fmac_f32_e32 v38, v40, v38
	v_mul_f32_e32 v40, v39, v38
	v_fma_f32 v41, -v36, v40, v39
	v_fmac_f32_e32 v40, v41, v38
	v_fma_f32 v36, -v36, v40, v39
	v_div_fmas_f32 v36, v36, v38, v40
	v_div_fixup_f32 v31, v36, v31, v249
	ds_write_b32 v116, v31 offset:768
	s_waitcnt vmcnt(4)
	v_mul_f32_e32 v36, 0xbfb8aa3b, v250
	v_exp_f32_e32 v36, v36
	s_nop 0
	v_add_f32_e32 v31, 1.0, v36
	v_div_scale_f32 v36, s[20:21], v31, v31, v250
	v_rcp_f32_e32 v38, v36
	v_div_scale_f32 v39, vcc, v250, v31, v250
	v_fma_f32 v40, -v36, v38, 1.0
	v_fmac_f32_e32 v38, v40, v38
	v_mul_f32_e32 v40, v39, v38
	v_fma_f32 v41, -v36, v40, v39
	v_fmac_f32_e32 v40, v41, v38
	v_fma_f32 v36, -v36, v40, v39
	v_div_fmas_f32 v36, v36, v38, v40
	v_div_fixup_f32 v31, v36, v31, v250
	ds_write_b32 v116, v31 offset:1024
	s_waitcnt vmcnt(3)
	v_mul_f32_e32 v36, 0xbfb8aa3b, v251
	v_exp_f32_e32 v36, v36
	s_nop 0
	v_add_f32_e32 v31, 1.0, v36
	v_div_scale_f32 v36, s[20:21], v31, v31, v251
	v_rcp_f32_e32 v38, v36
	v_div_scale_f32 v39, vcc, v251, v31, v251
	v_fma_f32 v40, -v36, v38, 1.0
	v_fmac_f32_e32 v38, v40, v38
	v_mul_f32_e32 v40, v39, v38
	v_fma_f32 v41, -v36, v40, v39
	v_fmac_f32_e32 v40, v41, v38
	v_fma_f32 v36, -v36, v40, v39
	v_div_fmas_f32 v36, v36, v38, v40
	v_div_fixup_f32 v31, v36, v31, v251
	ds_write_b32 v116, v31 offset:1280
	s_waitcnt vmcnt(2)
	v_mul_f32_e32 v36, 0xbfb8aa3b, v252
	v_exp_f32_e32 v36, v36
	s_nop 0
	v_add_f32_e32 v31, 1.0, v36
	v_div_scale_f32 v36, s[20:21], v31, v31, v252
	v_rcp_f32_e32 v38, v36
	v_div_scale_f32 v39, vcc, v252, v31, v252
	v_fma_f32 v40, -v36, v38, 1.0
	v_fmac_f32_e32 v38, v40, v38
	v_mul_f32_e32 v40, v39, v38
	v_fma_f32 v41, -v36, v40, v39
	v_fmac_f32_e32 v40, v41, v38
	v_fma_f32 v36, -v36, v40, v39
	v_div_fmas_f32 v36, v36, v38, v40
	v_div_fixup_f32 v31, v36, v31, v252
	ds_write_b32 v116, v31 offset:1536
	s_waitcnt vmcnt(1)
	v_mul_f32_e32 v36, 0xbfb8aa3b, v253
	v_exp_f32_e32 v36, v36
	s_nop 0
	v_add_f32_e32 v31, 1.0, v36
	v_div_scale_f32 v36, s[20:21], v31, v31, v253
	v_rcp_f32_e32 v38, v36
	v_div_scale_f32 v39, vcc, v253, v31, v253
	v_fma_f32 v40, -v36, v38, 1.0
	v_fmac_f32_e32 v38, v40, v38
	v_mul_f32_e32 v40, v39, v38
	v_fma_f32 v41, -v36, v40, v39
	v_fmac_f32_e32 v40, v41, v38
	v_fma_f32 v36, -v36, v40, v39
	v_div_fmas_f32 v36, v36, v38, v40
	v_div_fixup_f32 v31, v36, v31, v253
	ds_write_b32 v116, v31 offset:1792
	s_waitcnt vmcnt(0)
	v_mul_f32_e32 v36, 0xbfb8aa3b, v254
	v_exp_f32_e32 v36, v36
	s_nop 0
	v_add_f32_e32 v31, 1.0, v36
	v_div_scale_f32 v36, s[20:21], v31, v31, v254
	v_rcp_f32_e32 v38, v36
	v_div_scale_f32 v39, vcc, v254, v31, v254
	v_fma_f32 v40, -v36, v38, 1.0
	v_fmac_f32_e32 v38, v40, v38
	v_mul_f32_e32 v40, v39, v38
	v_fma_f32 v41, -v36, v40, v39
	v_fmac_f32_e32 v40, v41, v38
	v_fma_f32 v36, -v36, v40, v39
	v_div_fmas_f32 v36, v36, v38, v40
	v_div_fixup_f32 v31, v36, v31, v254
	ds_write_b32 v116, v31 offset:2048
